# static s_setprio 1 for waves 0-3 (other half) during both work-queue phases, for comparison with the waves 4-7 variant
# baseline (speedup 1.0000x reference)
.LBB0_646:
	s_or_b64 exec, exec, s[4:5]
	s_waitcnt lgkmcnt(0)
	s_barrier
	v_readfirstlane_b32 s30, v148
	s_lshr_b32 s30, s30, 6
	s_cmp_lt_u32 s30, 4
	s_cbranch_scc0 .Lprio_q1_skip
	s_setprio 1
